# rows loop: eight s_nop pads before permlane32 swaps removed where the two preceding instructions provably do not write the operands
# speedup vs baseline: 1.0025x; 1.0025x over previous
.Lp0rows_nopf:
	s_waitcnt lgkmcnt(1)
	v_fmac_f32_e32 v23, v230, v0
	v_fma_f32 v29, v232, v72, 0
	v_fma_f32 v62, v224, v188, 0
	v_fma_f32 v55, v232, v192, 0
	v_fmac_f32_e32 v52, v226, v18
	v_fmac_f32_e32 v40, v227, v11
	v_fmac_f32_e32 v32, v235, v15
	v_fmac_f32_e32 v54, v226, v154
	v_fmac_f32_e32 v61, v234, v158
	v_fmac_f32_e32 v53, v227, v139
	v_fmac_f32_e32 v35, v235, v143
	v_add_f32_e32 v16, v34, v43
	v_fmac_f32_e32 v23, v231, v1
	v_fmac_f32_e32 v29, v233, v73
	v_fma_f32 v25, v224, v80, 0
	v_fma_f32 v30, v232, v84, 0
	v_fmac_f32_e32 v62, v225, v189
	v_fmac_f32_e32 v55, v233, v193
	v_fma_f32 v63, v224, v200, 0
	v_fma_f32 v65, v232, v246, 0
	v_fmac_f32_e32 v52, v227, v19
	v_add_f32_e32 v9, v40, v32
	v_fmac_f32_e32 v54, v227, v155
	v_fmac_f32_e32 v61, v235, v159
	v_add_f32_e32 v17, v53, v35
	v_fmac_f32_e32 v23, v226, v2
	v_permlane32_swap_b32_e32 v8, v16
	v_fma_f32 v31, v224, v92, 0
	v_fma_f32 v26, v232, v100, 0
	v_fmac_f32_e32 v29, v228, v74
	v_fmac_f32_e32 v25, v225, v81
	v_fmac_f32_e32 v30, v233, v85
	v_fmac_f32_e32 v62, v222, v190
	v_fmac_f32_e32 v55, v228, v194
	v_fmac_f32_e32 v63, v225, v201
	v_fmac_f32_e32 v65, v233, v247
	v_add_f32_e32 v10, v52, v60
	v_add_f32_e32 v18, v54, v61
	v_fmac_f32_e32 v23, v227, v3
	v_permlane32_swap_b32_e32 v9, v17
	v_fmac_f32_e32 v31, v225, v93
	v_fmac_f32_e32 v26, v233, v101
	v_fmac_f32_e32 v64, v223, v67
	v_fmac_f32_e32 v29, v229, v75
	v_fmac_f32_e32 v25, v222, v82
	v_fmac_f32_e32 v30, v228, v86
	v_fmac_f32_e32 v62, v223, v191
	v_fmac_f32_e32 v55, v229, v195
	v_fmac_f32_e32 v63, v222, v202
	v_fmac_f32_e32 v65, v228, v248
	s_waitcnt lgkmcnt(0)
	v_fmac_f32_e32 v24, v236, v4
	v_permlane32_swap_b32_e32 v10, v18
	v_fmac_f32_e32 v31, v222, v94
	v_fmac_f32_e32 v26, v228, v102
	v_fmac_f32_e32 v64, v230, v36
	v_fmac_f32_e32 v29, v236, v44
	v_fmac_f32_e32 v25, v223, v83
	v_fmac_f32_e32 v30, v229, v87
	v_fmac_f32_e32 v62, v230, v172
	v_fmac_f32_e32 v55, v236, v180
	v_fmac_f32_e32 v63, v223, v203
	v_fmac_f32_e32 v65, v229, v249
	v_fmac_f32_e32 v31, v223, v95
	v_fmac_f32_e32 v26, v229, v103
	v_fmac_f32_e32 v64, v231, v37
	v_fmac_f32_e32 v29, v237, v45
	v_fmac_f32_e32 v25, v230, v48
	v_fmac_f32_e32 v30, v236, v56
	v_fmac_f32_e32 v62, v231, v173
	v_fmac_f32_e32 v55, v237, v181
	v_fmac_f32_e32 v63, v230, v196
	v_fmac_f32_e32 v65, v236, v204
	v_fmac_f32_e32 v31, v230, v68
	v_fmac_f32_e32 v26, v236, v76
	v_fmac_f32_e32 v64, v226, v38
	v_fmac_f32_e32 v29, v234, v46
	v_fmac_f32_e32 v25, v231, v49
	v_fmac_f32_e32 v30, v237, v57
	v_fmac_f32_e32 v62, v226, v174
	v_fmac_f32_e32 v55, v234, v182
	v_fmac_f32_e32 v63, v231, v197
	v_fmac_f32_e32 v65, v237, v205
	v_fmac_f32_e32 v31, v231, v69
	v_fmac_f32_e32 v26, v237, v77
	v_fmac_f32_e32 v64, v227, v39
	v_fmac_f32_e32 v29, v235, v47
	v_fmac_f32_e32 v25, v226, v50
	v_fmac_f32_e32 v30, v234, v58
	v_fmac_f32_e32 v62, v227, v175
	v_fmac_f32_e32 v55, v235, v183
	v_fmac_f32_e32 v63, v226, v198
	v_fmac_f32_e32 v65, v234, v206
	s_waitcnt lgkmcnt(2)
	v_add_f32_e32 v1, v8, v16
	v_fma_f32 v27, v224, v104, 0
	v_fma_f32 v33, v232, v112, 0
	v_fma_f32 v41, v224, v128, 0
	v_fma_f32 v42, v232, v132, 0
	v_fmac_f32_e32 v31, v226, v70
	v_fmac_f32_e32 v26, v234, v78
	v_add_f32_e32 v11, v64, v29
	v_fmac_f32_e32 v25, v227, v51
	v_fmac_f32_e32 v30, v235, v59
	v_add_f32_e32 v19, v62, v55
	v_fmac_f32_e32 v63, v227, v199
	v_fmac_f32_e32 v65, v235, v207
	s_waitcnt lgkmcnt(1)
	v_add_f32_e32 v2, v9, v17
	v_fmac_f32_e32 v27, v225, v105
	v_fmac_f32_e32 v33, v233, v113
	v_fmac_f32_e32 v41, v225, v129
	v_fmac_f32_e32 v42, v233, v133
	v_fmac_f32_e32 v31, v227, v71
	v_fmac_f32_e32 v26, v235, v79
	v_add_f32_e32 v12, v25, v30
	v_add_f32_e32 v20, v63, v65
	v_fmac_f32_e32 v24, v237, v5
	s_waitcnt lgkmcnt(0)
	v_add_f32_e32 v3, v10, v18
	v_permlane32_swap_b32_e32 v11, v19
	v_fmac_f32_e32 v27, v222, v106
	v_fmac_f32_e32 v33, v228, v114
	v_fmac_f32_e32 v41, v222, v130
	v_fmac_f32_e32 v42, v228, v134
	v_add_f32_e32 v13, v31, v26
	v_add_f32_e32 v21, v66, v21
	v_fmac_f32_e32 v24, v234, v6
	v_permlane32_swap_b32_e32 v12, v20
	v_fmac_f32_e32 v27, v223, v107
	v_fmac_f32_e32 v33, v229, v115
	v_fmac_f32_e32 v41, v223, v131
	v_fmac_f32_e32 v42, v229, v135
	v_fmac_f32_e32 v24, v235, v7
	v_permlane32_swap_b32_e32 v13, v21
	v_fmac_f32_e32 v27, v230, v88
	v_fmac_f32_e32 v33, v236, v96
	v_fmac_f32_e32 v41, v230, v108
	v_fmac_f32_e32 v42, v236, v116
	v_fmac_f32_e32 v27, v231, v89
	v_fmac_f32_e32 v33, v237, v97
	v_fmac_f32_e32 v41, v231, v109
	v_fmac_f32_e32 v42, v237, v117
	v_fmac_f32_e32 v27, v226, v90
	v_fmac_f32_e32 v33, v234, v98
	v_fmac_f32_e32 v41, v226, v110
	v_fmac_f32_e32 v42, v234, v118
	v_fmac_f32_e32 v27, v227, v91
	v_fmac_f32_e32 v33, v235, v99
	v_fmac_f32_e32 v41, v227, v111
	v_fmac_f32_e32 v42, v235, v119
	s_waitcnt lgkmcnt(2)
	v_add_f32_e32 v4, v11, v19
	v_add_f32_e32 v14, v27, v33
	v_add_f32_e32 v15, v41, v42
	v_add_f32_e32 v0, v23, v24
	s_waitcnt lgkmcnt(1)
	v_add_f32_e32 v5, v12, v20
	s_waitcnt lgkmcnt(0)
	v_add_f32_e32 v6, v13, v21
	v_permlane32_swap_b32_e32 v14, v22
	v_permlane32_swap_b32_e32 v15, v0
	s_waitcnt lgkmcnt(1)
	v_add_f32_e32 v7, v14, v22
	s_waitcnt lgkmcnt(0)
	v_add_f32_e32 v0, v15, v0
	s_nop 1
	v_permlane16_swap_b32_e32 v1, v5
	v_permlane16_swap_b32_e32 v2, v6
	v_permlane16_swap_b32_e32 v3, v7
	v_permlane16_swap_b32_e32 v4, v0
	v_add_f32_e32 v1, v1, v5
	v_add_f32_e32 v2, v2, v6
	v_add_f32_e32 v3, v3, v7
	v_add_f32_e32 v0, v4, v0
	v_cndmask_b32_e64 v4, v1, v3, s[12:13]
	v_cndmask_b32_e64 v5, v2, v0, s[12:13]
	v_cndmask_b32_e64 v1, v3, v1, s[12:13]
	v_cndmask_b32_e64 v0, v0, v2, s[12:13]
	s_nop 1
	v_add_f32_dpp v1, v4, v1 row_ror:8 row_mask:0xf bank_mask:0xf
	v_add_f32_dpp v0, v5, v0 row_ror:8 row_mask:0xf bank_mask:0xf
	v_cndmask_b32_e64 v2, v1, v0, s[14:15]
	v_cndmask_b32_e64 v0, v0, v1, s[14:15]
	s_nop 1
	v_mov_b32_dpp v3, v2 row_shl:4 row_mask:0xf bank_mask:0x5
	v_mov_b32_dpp v3, v2 row_shr:4 row_mask:0xf bank_mask:0xa
	s_nop 1
	v_add_f32_e32 v0, v0, v3
	s_nop 1
	v_add_f32_dpp v0, v0, v0 quad_perm:[2,3,0,1] row_mask:0xf bank_mask:0xf
	s_nop 1
	v_add_f32_dpp v0, v0, v0 quad_perm:[1,0,3,2] row_mask:0xf bank_mask:0xf
	s_and_saveexec_b64 s[18:19], s[16:17]
	s_cbranch_execz .LBB0_109
	s_ashr_i32 s44, s36, 8
	s_and_b32 s51, s36, 0xfff
	v_add_f32_e32 v2, v0, v245
	v_mul_f32_e64 v0, |v2|, s50
	v_exp_f32_e32 v3, v0
	v_and_or_b32 v0, s44, -16, v243
	v_ashrrev_i32_e32 v1, 31, v0
	v_lshlrev_b64 v[0:1], 14, v[0:1]
	v_add_f32_e32 v3, 1.0, v3
	v_log_f32_e32 v3, v3
	s_lshl_b32 s44, s51, 2
	v_lshl_add_u64 v[0:1], s[42:43], 0, v[0:1]
	v_min_f32_e32 v2, 0, v2
	v_fmac_f32_e32 v2, 0xbf317218, v3
	v_lshl_add_u64 v[0:1], v[0:1], 0, s[44:45]
	global_store_dword v[0:1], v2, off
	s_branch .LBB0_109
